# neighbourhood attention tile loop: the eight masked bias gathers of a key-row tile issued together and waited on once (were load-wait pairs)
# speedup vs baseline: 1.0125x; 1.0076x over previous
.LBB0_659:
	s_bitcmp1_b32 s48, 0
	s_cselect_b32 s40, 0x4800, 0
	s_add_i32 s56, s40, 16
	s_cmp_gt_u32 s48, 3
	s_mov_b64 s[40:41], -1
	s_cbranch_scc0 .LBB0_685
	s_add_i32 s40, s52, s48
	v_cmp_ge_i32_e32 vcc, s40, v99
	v_cmp_lt_i32_e64 s[40:41], s40, v100
	v_mov_b64_e32 v[16:17], v[36:37]
	v_mov_b64_e32 v[4:5], v[40:41]
	v_mov_b64_e32 v[8:9], v[44:45]
	v_mov_b64_e32 v[12:13], v[48:49]
	s_and_b64 s[48:49], vcc, s[40:41]
	v_mov_b32_e32 v56, v109
	v_mov_b32_e32 v95, v110
	v_mov_b64_e32 v[18:19], v[38:39]
	v_mov_b64_e32 v[6:7], v[42:43]
	v_mov_b64_e32 v[10:11], v[46:47]
	v_mov_b64_e32 v[14:15], v[50:51]
	s_and_saveexec_b64 s[40:41], s[48:49]
	s_cbranch_execz .LBB0_680
	v_ashrrev_i32_e32 v95, 31, v94
	v_mov_b32_e32 v14, 0xff800000
	v_mov_b32_e32 v0, 0xff800000
	v_mov_b32_e32 v15, 0xff800000
	v_mov_b32_e32 v112, 0xff800000
	v_mov_b32_e32 v111, 0xff800000
	v_mov_b32_e32 v113, 0xff800000
	v_mov_b32_e32 v114, 0xff800000
	v_mov_b32_e32 v115, 0xff800000
	s_mov_b64 s[48:49], exec
	s_and_b64 exec, s[48:49], s[14:15]
	s_cbranch_execz .Lna_b0
	v_lshl_add_u64 v[2:3], v[94:95], 0, v[78:79]
	v_lshl_add_u64 v[2:3], v[2:3], 2, s[12:13]
	global_load_dword v126, v[2:3], off offset:868
.Lna_b0:
	s_and_b64 exec, s[48:49], s[22:23]
	s_cbranch_execz .Lna_b1
	v_lshl_add_u64 v[2:3], v[94:95], 0, v[76:77]
	v_lshl_add_u64 v[2:3], v[2:3], 2, s[12:13]
	global_load_dword v127, v[2:3], off offset:868
.Lna_b1:
	s_and_b64 exec, s[48:49], s[24:25]
	s_cbranch_execz .Lna_b2
	v_lshl_add_u64 v[2:3], v[94:95], 0, v[82:83]
	v_lshl_add_u64 v[2:3], v[2:3], 2, s[12:13]
	global_load_dword v128, v[2:3], off offset:868
.Lna_b2:
	s_and_b64 exec, s[48:49], s[26:27]
	s_cbranch_execz .Lna_b3
	v_lshl_add_u64 v[2:3], v[94:95], 0, v[80:81]
	v_lshl_add_u64 v[2:3], v[2:3], 2, s[12:13]
	global_load_dword v129, v[2:3], off offset:868
.Lna_b3:
	s_and_b64 exec, s[48:49], s[28:29]
	s_cbranch_execz .Lna_b4
	v_lshl_add_u64 v[2:3], v[94:95], 0, v[86:87]
	v_lshl_add_u64 v[2:3], v[2:3], 2, s[12:13]
	global_load_dword v130, v[2:3], off offset:868
.Lna_b4:
	s_and_b64 exec, s[48:49], s[30:31]
	s_cbranch_execz .Lna_b5
	v_lshl_add_u64 v[2:3], v[94:95], 0, v[84:85]
	v_lshl_add_u64 v[2:3], v[2:3], 2, s[12:13]
	global_load_dword v131, v[2:3], off offset:868
.Lna_b5:
	s_and_b64 exec, s[48:49], s[42:43]
	s_cbranch_execz .Lna_b6
	v_lshl_add_u64 v[2:3], v[94:95], 0, v[90:91]
	v_lshl_add_u64 v[2:3], v[2:3], 2, s[12:13]
	global_load_dword v132, v[2:3], off offset:868
.Lna_b6:
	s_and_b64 exec, s[48:49], s[44:45]
	s_cbranch_execz .Lna_b7
	v_lshl_add_u64 v[2:3], v[94:95], 0, v[88:89]
	v_lshl_add_u64 v[2:3], v[2:3], 2, s[12:13]
	global_load_dword v133, v[2:3], off offset:868
.Lna_b7:
	s_mov_b64 exec, s[48:49]
	s_waitcnt vmcnt(0) lgkmcnt(0)
	v_mul_f32_e32 v126, 0x3fb8aa3b, v126
	v_cndmask_b32_e64 v0, v0, v126, s[14:15]
	v_mul_f32_e32 v127, 0x3fb8aa3b, v127
	v_cndmask_b32_e64 v14, v14, v127, s[22:23]
	v_mul_f32_e32 v128, 0x3fb8aa3b, v128
	v_cndmask_b32_e64 v112, v112, v128, s[24:25]
	v_mul_f32_e32 v129, 0x3fb8aa3b, v129
	v_cndmask_b32_e64 v15, v15, v129, s[26:27]
	v_mul_f32_e32 v130, 0x3fb8aa3b, v130
	v_cndmask_b32_e64 v113, v113, v130, s[28:29]
	v_mul_f32_e32 v131, 0x3fb8aa3b, v131
	v_cndmask_b32_e64 v111, v111, v131, s[30:31]
	v_mul_f32_e32 v132, 0x3fb8aa3b, v132
	v_cndmask_b32_e64 v115, v115, v132, s[42:43]
	v_mul_f32_e32 v133, 0x3fb8aa3b, v133
	v_cndmask_b32_e64 v114, v114, v133, s[44:45]
.LBB0_677:
	v_add3_u32 v16, s56, v101, v102
	ds_read_b128 v[2:5], v16
	ds_read_b128 v[6:9], v16 offset:64
	ds_read_b128 v[10:13], v16 offset:2304
	ds_read_b128 v[16:19], v16 offset:2368
	v_cmp_lt_i32_e32 vcc, v222, v220
	v_mov_b64_e32 v[62:63], v[42:43]
	s_waitcnt lgkmcnt(0)
	v_mfma_f32_16x16x32_bf16 v[2:5], v[2:5], v[20:23], 0
	v_mov_b64_e32 v[66:67], v[46:47]
	v_mov_b64_e32 v[58:59], v[50:51]
	v_mov_b32_e32 v95, v110
	v_mfma_f32_16x16x32_bf16 v[10:13], v[10:13], v[20:23], 0
	v_mov_b64_e32 v[60:61], v[40:41]
	v_mov_b64_e32 v[64:65], v[44:45]
	v_mov_b64_e32 v[56:57], v[48:49]
	v_mfma_f32_16x16x32_bf16 v[2:5], v[6:9], v[24:27], v[2:5]
	v_add3_u32 v6, s56, v103, v104
	v_add3_u32 v52, v6, v105, v106
	v_add3_u32 v53, v6, v107, v108
	v_mfma_f32_16x16x32_bf16 v[6:9], v[16:19], v[24:27], v[10:13]
	v_mov_b32_e32 v116, v109
	s_nop 2
	v_fmac_f32_e32 v0, 0x3e38aa3b, v2
	v_fmac_f32_e32 v112, 0x3e38aa3b, v3
	v_fmac_f32_e32 v113, 0x3e38aa3b, v4
	v_fmac_f32_e32 v115, 0x3e38aa3b, v5
	v_fmac_f32_e32 v111, 0x3e38aa3b, v8
	v_fmac_f32_e32 v114, 0x3e38aa3b, v9
	v_fmac_f32_e32 v14, 0x3e38aa3b, v6
	v_fmac_f32_e32 v15, 0x3e38aa3b, v7
	v_max_f32_e32 v4, v111, v114
	v_max_f32_e32 v2, v0, v112
	v_max_f32_e32 v3, v113, v115
	v_max3_f32 v4, v14, v15, v4
	v_max3_f32 v4, v2, v3, v4
	v_cndmask_b32_e32 v2, v219, v222, vcc
	v_lshlrev_b32_e32 v2, 2, v2
	ds_bpermute_b32 v5, v2, v4
	v_cmp_lt_i32_e32 vcc, v221, v220
	ds_read_b64 v[10:11], v52 offset:9216
	ds_read_b64 v[6:7], v52 offset:11520
	ds_read_b64 v[2:3], v52 offset:13824
	ds_read_b64 v[16:17], v52 offset:16128
	s_waitcnt lgkmcnt(0)
	v_max_f32_e32 v5, v5, v5
	v_max_f32_e32 v52, v4, v5
	v_cndmask_b32_e32 v4, v219, v221, vcc
	v_lshlrev_b32_e32 v4, 2, v4
	ds_bpermute_b32 v54, v4, v52
	ds_read_b64 v[12:13], v53 offset:9216
	ds_read_b64 v[8:9], v53 offset:11520
	ds_read_b64 v[4:5], v53 offset:13824
	ds_read_b64 v[18:19], v53 offset:16128
	s_waitcnt lgkmcnt(0)
	v_max3_f32 v117, v110, v52, v54
	v_mov_b64_e32 v[54:55], v[38:39]
	v_cmp_gt_f32_e32 vcc, v117, v110
	v_mov_b64_e32 v[52:53], v[36:37]
	s_cbranch_vccz .LBB0_679
	v_sub_f32_e32 v52, v110, v117
	v_exp_f32_e32 v52, v52
	v_mov_b32_e32 v95, v117
	v_mul_f32_e32 v116, v109, v52
	v_pk_mul_f32 v[58:59], v[50:51], v[52:53] op_sel_hi:[1,0]
	v_pk_mul_f32 v[56:57], v[48:49], v[52:53] op_sel_hi:[1,0]
	v_pk_mul_f32 v[66:67], v[46:47], v[52:53] op_sel_hi:[1,0]
	v_pk_mul_f32 v[64:65], v[44:45], v[52:53] op_sel_hi:[1,0]
	v_pk_mul_f32 v[62:63], v[42:43], v[52:53] op_sel_hi:[1,0]
	v_pk_mul_f32 v[60:61], v[40:41], v[52:53] op_sel_hi:[1,0]
	v_pk_mul_f32 v[54:55], v[38:39], v[52:53] op_sel_hi:[1,0]
	v_pk_mul_f32 v[52:53], v[36:37], v[52:53] op_sel_hi:[1,0]
